# attention full tiles: two pad nops before the row max removed (the sixteen fragment reads already cover the MFMA result distance)
# baseline (speedup 1.0000x reference)
.Lat2_main_2:
	v_add_u32_e32 v205, s59, v203
	ds_read_b128 v[116:119], v205 offset:0
	ds_read_b128 v[120:123], v205 offset:512
	ds_read_b128 v[124:127], v205 offset:2048
	ds_read_b128 v[128:131], v205 offset:2560
	ds_read_b128 v[132:135], v205 offset:4096
	ds_read_b128 v[136:139], v205 offset:4608
	ds_read_b128 v[140:143], v205 offset:6144
	ds_read_b128 v[144:147], v205 offset:6656
	s_nop 0
	s_add_i32 s4, s25, s16
	s_mov_b32 m0, s4
	s_lshl_b32 s5, s25, 1
	global_load_lds_dwordx4 v200, s[80:81]
	s_add_i32 s5, s5, s16
	s_add_i32 s5, s5, 0x8000
	s_mov_b32 m0, s5
	s_add_i32 s5, s5, 0x2000
	global_load_lds_dwordx4 v201, s[82:83]
	s_mov_b32 m0, s5
	s_nop 0
	global_load_lds_dwordx4 v202, s[82:83]
	s_add_u32 s80, s80, 0x10000
	s_addc_u32 s81, s81, 0
	s_add_u32 s82, s82, 0x10000
	s_addc_u32 s83, s83, 0
	s_lshl_b32 s7, s59, 1
	v_add_u32_e32 v206, s7, v204
	s_waitcnt lgkmcnt(6)
	v_mfma_f32_32x32x16_bf16 v[64:79], v[116:119], v[148:151], v[100:115]
	v_mfma_f32_32x32x16_bf16 v[80:95], v[120:123], v[148:151], v[100:115]
	s_waitcnt lgkmcnt(4)
	v_mfma_f32_32x32x16_bf16 v[64:79], v[124:127], v[152:155], v[64:79]
	v_mfma_f32_32x32x16_bf16 v[80:95], v[128:131], v[152:155], v[80:95]
	s_waitcnt lgkmcnt(2)
	v_mfma_f32_32x32x16_bf16 v[64:79], v[132:135], v[156:159], v[64:79]
	v_mfma_f32_32x32x16_bf16 v[80:95], v[136:139], v[156:159], v[80:95]
	s_waitcnt lgkmcnt(0)
	v_mfma_f32_32x32x16_bf16 v[64:79], v[140:143], v[160:163], v[64:79]
	v_mfma_f32_32x32x16_bf16 v[80:95], v[144:147], v[160:163], v[80:95]
	ds_read_b64_tr_b16 v[164:165], v206 offset:0
	ds_read_b64_tr_b16 v[166:167], v206 offset:512
	ds_read_b64_tr_b16 v[168:169], v206 offset:4096
	ds_read_b64_tr_b16 v[170:171], v206 offset:4608
	ds_read_b64_tr_b16 v[172:173], v206 offset:8192
	ds_read_b64_tr_b16 v[174:175], v206 offset:8704
	ds_read_b64_tr_b16 v[176:177], v206 offset:12288
	ds_read_b64_tr_b16 v[178:179], v206 offset:12800
	ds_read_b64_tr_b16 v[180:181], v206 offset:1024
	ds_read_b64_tr_b16 v[182:183], v206 offset:1536
	ds_read_b64_tr_b16 v[184:185], v206 offset:5120
	ds_read_b64_tr_b16 v[186:187], v206 offset:5632
	ds_read_b64_tr_b16 v[188:189], v206 offset:9216
	ds_read_b64_tr_b16 v[190:191], v206 offset:9728
	ds_read_b64_tr_b16 v[192:193], v206 offset:13312
	ds_read_b64_tr_b16 v[194:195], v206 offset:13824
	v_max3_f32 v215, v64, v65, v80
	v_max3_f32 v216, v66, v67, v81
	v_max3_f32 v215, v215, v82, v83
	v_max3_f32 v216, v216, v68, v69
	v_max3_f32 v215, v215, v70, v71
	v_max3_f32 v216, v216, v84, v85
	v_max3_f32 v215, v215, v86, v87
	v_max3_f32 v216, v216, v72, v73
	v_max3_f32 v215, v215, v74, v75
	v_max3_f32 v216, v216, v88, v89
	v_max3_f32 v215, v215, v90, v91
	v_max3_f32 v216, v216, v76, v77
	v_max3_f32 v215, v215, v78, v79
	v_max3_f32 v216, v216, v92, v93
	v_max3_f32 v215, v215, v94, v95
	v_max_f32_e32 v214, v215, v216
	v_mov_b32_e32 v215, v214
	s_nop 1
	v_permlane32_swap_b32_e32 v214, v215
	s_nop 0
	v_max_f32_e32 v214, v214, v215
	v_cmp_lt_f32_e32 vcc, s62, v214
	s_cmp_lg_u64 vcc, 0
	s_cbranch_scc1 .Lat2_resc_7
